# P3 RWKV loader waves fetch raw chunk inputs by coalesced LDS-DMA (12 full-line instructions per chunk and CU instead of 24 scattered 16-line loads) into a 3-slot LDS ring, read back with ds_read_b64
# baseline (speedup 1.0000x reference)
; template <bool RWKV> __device__ __forceinline__ void scan_load_issue(ScanLd& L, const ScanSrc& S, int chunk, int lt) {
;     const int lw = lt >> 6, lane = lt & 63, sl = lane >> 2, col = 16 * lw + 4 * (lane & 3), s = chunk * SC_CH + sl; const size_t tok = (size_t)(S.tokbase + (S.rev ? T_SEQ - 1 - s : s));
;     L.rd = *(const u32x2*)(S.v[0] + tok * S.ld[0] + col); L.rk = *(const u32x2*)(S.v[1] + tok * S.ld[1] + col); L.rr = *(const u32x2*)(S.v[4] + tok * S.ld[4] + col); L.rv = *(const u32x2*)(S.v[5] + tok * S.ld[5] + col);
;     L.rkk = L.rk; L.rnb = L.rk;
;     if (RWKV) { L.rkk = *(const u32x2*)(S.v[2] + tok * S.ld[2] + col); L.rnb = *(const u32x2*)(S.v[3] + tok * S.ld[3] + col); }
; }
; template <bool RWKV> __device__ __forceinline__ void scan_item(LAS unsigned char* lds, const ScanSrc& S, int wid, int lane) {
;     f32x16 T[2];
; #pragma unroll
;     for (int a = 0; a < 2; ++a)
; #pragma unroll
;         for (int i = 0; i < 16; ++i) T[a][i] = 0.f;
;     const bool is_ld = (wid == 4) | (wid == 5) | (wid == 3) | (wid == 7); const bool is_prep = wid == 2;
;     const int lt = (wid == 4 ? 0 : wid == 5 ? 64 : wid == 3 ? 128 : 192) + lane;
;     ScanLd L;
;     constexpr int NCH = T_SEQ / SC_CH;
;     ...
;     const bool is_inv = wid == 6;
;     if (is_ld) { scan_load_issue<RWKV>(L, S, 0, lt); scan_load_finish<RWKV>(lds, L, lt); scan_load_issue<RWKV>(L, S, 1, lt); scan_load_finish<RWKV>(lds + SC_BUF, L, lt);
;                  scan_load_issue<RWKV>(L, S, 2, lt); scan_load_finish<RWKV>(lds + 2 * SC_BUF, L, lt); scan_load_issue<RWKV>(L, S, 3, lt); }
.LBB0_611:
	s_or_b64 exec, exec, s[72:73]
	s_lshl_b32 s72, s89, 25
	s_add_u32 s72, s56, s72
	s_addc_u32 s73, s57, 0
	s_add_u32 s72, s72, s93
	v_lshlrev_b32_e32 v74, 1, v20
	s_addc_u32 s73, s73, 0
	s_lshr_b32 s89, s81, 2
	v_lshl_add_u64 v[88:89], s[0:1], 0, v[74:75]
	s_lshl_b64 s[0:1], s[86:87], 1
	v_or_b32_e32 v0, s89, v122
	s_add_u32 s0, s72, s0
	v_lshlrev_b32_e32 v182, 1, v0
	v_mul_u32_u24_e32 v183, 0x50, v0
	v_mul_u32_u24_e32 v184, 48, v0
	v_mad_u32_u24 v185, v0, s88, s88
	v_mad_u32_u24 v186, v0, s88, v180
	v_mad_u32_u24 v187, v0, s88, v181
	v_lshlrev_b32_e32 v188, 2, v0
	v_lshl_add_u64 v[90:91], s[60:61], 0, v[74:75]
	v_lshl_add_u64 v[92:93], s[68:69], 0, v[74:75]
	v_lshl_add_u64 v[94:95], s[70:71], 0, v[74:75]
	v_lshl_add_u64 v[96:97], s[42:43], 0, v[74:75]
	v_lshl_add_u64 v[98:99], s[66:67], 0, v[74:75]
	s_addc_u32 s1, s73, s1
	v_lshlrev_b32_e32 v74, 1, v72
	s_ashr_i32 s66, s83, 31
	v_add_u32_e32 v0, s81, v73
	s_waitcnt lgkmcnt(0)
	s_barrier
	v_lshl_add_u64 v[100:101], s[0:1], 0, v[74:75]
	s_and_b64 s[0:1], s[40:41], exec
	s_movk_i32 s89, 0x200
	v_bfe_u32 v0, v0, 2, 4
	s_cselect_b32 s0, s89, 0xfffffe00
	v_or_b32_e32 v74, 64, v0
	v_sub_u32_e32 v189, 0, v0
	v_mov_b32_e32 v0, 0
	v_mul_hi_i32_i24_e32 v103, s0, v138
	v_mul_i32_i24_e32 v102, s0, v138
	v_mul_hi_i32_i24_e32 v105, s0, v139
	v_mul_i32_i24_e32 v104, s0, v139
	v_mul_hi_i32_i24_e32 v107, s0, v140
	v_mul_i32_i24_e32 v106, s0, v140
	v_mul_hi_i32_i24_e32 v109, s0, v141
	v_mul_i32_i24_e32 v108, s0, v141
	v_mul_hi_i32_i24_e32 v111, s0, v142
	v_mul_i32_i24_e32 v110, s0, v142
	v_mul_hi_i32_i24_e32 v113, s0, v143
	v_mul_i32_i24_e32 v112, s0, v143
	v_mul_hi_i32_i24_e32 v115, s0, v144
	v_mul_i32_i24_e32 v114, s0, v144
	v_mul_hi_i32_i24_e32 v117, s0, v145
	v_mul_i32_i24_e32 v116, s0, v145
	s_mov_b32 s67, 0
	s_movk_i32 s68, 0xfbf
	s_mov_b32 s69, 0
	s_mov_b32 s72, 0
	s_mov_b32 s70, 0
	v_mov_b32_e32 v1, v0
	v_mov_b32_e32 v2, v0
	v_mov_b32_e32 v3, v0
	v_mov_b32_e32 v4, v0
	v_mov_b32_e32 v5, v0
	v_mov_b32_e32 v6, v0
	v_mov_b32_e32 v7, v0
	v_mov_b32_e32 v8, v0
	v_mov_b32_e32 v9, v0
	v_mov_b32_e32 v10, v0
	v_mov_b32_e32 v11, v0
	v_mov_b32_e32 v12, v0
	v_mov_b32_e32 v13, v0
	v_mov_b32_e32 v14, v0
	v_mov_b32_e32 v15, v0
	v_mov_b32_e32 v16, v0
	v_mov_b32_e32 v17, v0
	v_mov_b32_e32 v18, v0
	v_mov_b32_e32 v19, v0
	v_mov_b32_e32 v20, v0
	v_mov_b32_e32 v21, v0
	v_mov_b32_e32 v22, v0
	v_mov_b32_e32 v23, v0
	v_mov_b32_e32 v24, v0
	v_mov_b32_e32 v25, v0
	v_mov_b32_e32 v26, v0
	v_mov_b32_e32 v27, v0
	v_mov_b32_e32 v28, v0
	v_mov_b32_e32 v29, v0
	v_mov_b32_e32 v30, v0
	v_mov_b32_e32 v31, v0
	v_and_b32_e32 v251, 3, v73
	v_and_b32_e32 v252, 48, v73
	v_add_u32_e32 v251, v251, v252
	v_add_u32_e32 v251, -4, v251
	v_and_b32_e32 v253, 16, v73
	v_cmp_ne_u32_e32 vcc, 0, v253
	v_and_b32_e32 v252, 3, v73
	v_add_u32_e32 v252, 28, v252
	v_cndmask_b32_e32 v251, v73, v251, vcc
	v_cndmask_b32_e64 v253, 0, 1.0, vcc
	v_cmp_lt_u32_e32 vcc, 31, v73
	v_lshlrev_b32_e32 v251, 2, v251
	v_lshlrev_b32_e32 v252, 2, v252
	v_cndmask_b32_e64 v245, 0, 1.0, vcc
	v_add_u32_e32 v248, v123, v182
	v_add_u32_e32 v249, v183, v127
	v_add_u32_e32 v250, v184, v127
	v_add_u32_e32 v33, 0xfbf, v189
	v_cndmask_b32_e64 v32, v33, v74, s[40:41]
	v_add_u32_e32 v32, s83, v32
	v_ashrrev_i32_e32 v33, 31, v32
	v_lshlrev_b64 v[34:35], 10, v[32:33]
	v_lshl_add_u64 v[234:235], v[88:89], 0, v[34:35]
	v_mad_i64_i32 v[236:237], s[0:1], v32, s79, v[90:91]
	v_mad_i64_i32 v[238:239], s[0:1], v32, s79, v[92:93]
	v_mad_i64_i32 v[240:241], s[0:1], v32, s79, v[94:95]
	v_lshl_add_u64 v[242:243], v[96:97], 0, v[34:35]
	v_lshl_add_u64 v[246:247], v[98:99], 0, v[34:35]
	s_and_b64 s[0:1], s[40:41], exec
	s_mov_b32 s98, 0x4000
	s_cselect_b32 s98, s98, 0xffffc000
	s_cselect_b32 s99, 0, -1
	s_mov_b32 s100, 0xc000
	s_cselect_b32 s100, s100, 0xffff4000
	s_cselect_b32 s101, 0, -1
	s_cmp_lt_i32 s3, 3
	s_cbranch_scc1 .Lrw_init_done
	s_cmp_eq_u32 s3, 6
	s_cbranch_scc1 .Lrw_init_done
	v_and_b32_e32 v14, 3, v73
	v_lshrrev_b32_e32 v15, 2, v73
	s_lshr_b32 s42, s81, 6
	s_and_b32 s42, s42, 3
	v_lshlrev_b32_e32 v16, 3, v14
	s_lshl_b32 s43, s42, 5
	v_add_u32_e32 v16, s43, v16
	v_sub_u32_e32 v17, 0, v15
	v_cndmask_b32_e64 v18, v15, v17, s[40:41]
	v_sub_u32_e32 v20, 0, v16
	v_ashrrev_i32_e32 v21, 31, v20
	v_lshrrev_b32_e32 v24, 3, v73
	v_and_b32_e32 v25, 7, v73
	v_xor_b32_e32 v25, v25, v24
	v_lshlrev_b32_e32 v26, 4, v25
	v_mov_b32_e32 v27, 0
	v_and_b32_e32 v28, 7, v15
	v_lshrrev_b32_e32 v29, 1, v14
	s_lshl_b32 s43, s42, 1
	v_add_u32_e32 v29, s43, v29
	v_xor_b32_e32 v29, v29, v28
	v_lshl_add_u32 v29, v28, 3, v29
	v_lshlrev_b32_e32 v29, 4, v29
	v_lshrrev_b32_e32 v30, 3, v15
	v_lshl_add_u32 v29, v30, 10, v29
	v_and_b32_e32 v30, 1, v14
	v_lshl_add_u32 v29, v30, 3, v29
	v_add_u32_e32 v12, 0x15800, v29
	s_cmp_lg_u32 s42, 0
	s_cbranch_scc1 .Lrw_dma_lw1
	s_movk_i32 s43, 0x400
	v_mad_i64_i32 v[22:23], s[0:1], v18, s43, v[234:235]
	v_lshl_add_u64 v[22:23], v[22:23], 0, v[20:21]
	v_mov_b32_e32 v30, v24
	v_sub_u32_e32 v31, 0, v30
	v_cndmask_b32_e64 v30, v31, v30, s[40:41]
	v_mad_i64_i32 v[0:1], s[0:1], v30, s43, v[22:23]
	v_lshl_add_u64 v[0:1], v[0:1], 0, v[26:27]
	v_mov_b32_e32 v6, s98
	v_mov_b32_e32 v7, s99
	s_movk_i32 s43, 0x400
	v_mad_i64_i32 v[22:23], s[0:1], v18, s43, v[234:235]
	v_lshl_add_u64 v[22:23], v[22:23], 0, v[20:21]
	v_add_u32_e32 v30, 8, v24
	v_sub_u32_e32 v31, 0, v30
	v_cndmask_b32_e64 v30, v31, v30, s[40:41]
	v_mad_i64_i32 v[2:3], s[0:1], v30, s43, v[22:23]
	v_lshl_add_u64 v[2:3], v[2:3], 0, v[26:27]
	v_mov_b32_e32 v8, s98
	v_mov_b32_e32 v9, s99
	s_movk_i32 s43, 0xc00
	v_mad_i64_i32 v[22:23], s[0:1], v18, s43, v[236:237]
	v_lshl_add_u64 v[22:23], v[22:23], 0, v[20:21]
	v_mov_b32_e32 v30, v24
	v_sub_u32_e32 v31, 0, v30
	v_cndmask_b32_e64 v30, v31, v30, s[40:41]
	v_mad_i64_i32 v[4:5], s[0:1], v30, s43, v[22:23]
	v_lshl_add_u64 v[4:5], v[4:5], 0, v[26:27]
	v_mov_b32_e32 v10, s100
	v_mov_b32_e32 v11, s101
	s_branch .Lrw_dma_set
; template <bool RWKV> __device__ __forceinline__ void scan_load_issue(ScanLd& L, const ScanSrc& S, int chunk, int lt) {
;     const int lw = lt >> 6, lane = lt & 63, sl = lane >> 2, col = 16 * lw + 4 * (lane & 3), s = chunk * SC_CH + sl; const size_t tok = (size_t)(S.tokbase + (S.rev ? T_SEQ - 1 - s : s));
;     L.rd = *(const u32x2*)(S.v[0] + tok * S.ld[0] + col); L.rk = *(const u32x2*)(S.v[1] + tok * S.ld[1] + col); L.rr = *(const u32x2*)(S.v[4] + tok * S.ld[4] + col); L.rv = *(const u32x2*)(S.v[5] + tok * S.ld[5] + col);
;     L.rkk = L.rk; L.rnb = L.rk;
;     if (RWKV) { L.rkk = *(const u32x2*)(S.v[2] + tok * S.ld[2] + col); L.rnb = *(const u32x2*)(S.v[3] + tok * S.ld[3] + col); }
; }
.Lrw_dma_lw1:
	s_cmp_lg_u32 s42, 1
	s_cbranch_scc1 .Lrw_dma_lw2
	s_movk_i32 s43, 0xc00
	v_mad_i64_i32 v[22:23], s[0:1], v18, s43, v[236:237]
	v_lshl_add_u64 v[22:23], v[22:23], 0, v[20:21]
	v_add_u32_e32 v30, 8, v24
	v_sub_u32_e32 v31, 0, v30
	v_cndmask_b32_e64 v30, v31, v30, s[40:41]
	v_mad_i64_i32 v[0:1], s[0:1], v30, s43, v[22:23]
	v_lshl_add_u64 v[0:1], v[0:1], 0, v[26:27]
	v_mov_b32_e32 v6, s100
	v_mov_b32_e32 v7, s101
	s_movk_i32 s43, 0xc00
	v_mad_i64_i32 v[22:23], s[0:1], v18, s43, v[238:239]
	v_lshl_add_u64 v[22:23], v[22:23], 0, v[20:21]
	v_mov_b32_e32 v30, v24
	v_sub_u32_e32 v31, 0, v30
	v_cndmask_b32_e64 v30, v31, v30, s[40:41]
	v_mad_i64_i32 v[2:3], s[0:1], v30, s43, v[22:23]
	v_lshl_add_u64 v[2:3], v[2:3], 0, v[26:27]
	v_mov_b32_e32 v8, s100
	v_mov_b32_e32 v9, s101
	s_movk_i32 s43, 0xc00
	v_mad_i64_i32 v[22:23], s[0:1], v18, s43, v[238:239]
	v_lshl_add_u64 v[22:23], v[22:23], 0, v[20:21]
	v_add_u32_e32 v30, 8, v24
	v_sub_u32_e32 v31, 0, v30
	v_cndmask_b32_e64 v30, v31, v30, s[40:41]
	v_mad_i64_i32 v[4:5], s[0:1], v30, s43, v[22:23]
	v_lshl_add_u64 v[4:5], v[4:5], 0, v[26:27]
	v_mov_b32_e32 v10, s100
	v_mov_b32_e32 v11, s101
	s_branch .Lrw_dma_set
.Lrw_dma_lw2:
	s_cmp_lg_u32 s42, 2
	s_cbranch_scc1 .Lrw_dma_lw3
	s_movk_i32 s43, 0xc00
	v_mad_i64_i32 v[22:23], s[0:1], v18, s43, v[240:241]
	v_lshl_add_u64 v[22:23], v[22:23], 0, v[20:21]
	v_mov_b32_e32 v30, v24
	v_sub_u32_e32 v31, 0, v30
	v_cndmask_b32_e64 v30, v31, v30, s[40:41]
	v_mad_i64_i32 v[0:1], s[0:1], v30, s43, v[22:23]
	v_lshl_add_u64 v[0:1], v[0:1], 0, v[26:27]
	v_mov_b32_e32 v6, s100
	v_mov_b32_e32 v7, s101
	s_movk_i32 s43, 0xc00
	v_mad_i64_i32 v[22:23], s[0:1], v18, s43, v[240:241]
	v_lshl_add_u64 v[22:23], v[22:23], 0, v[20:21]
	v_add_u32_e32 v30, 8, v24
	v_sub_u32_e32 v31, 0, v30
	v_cndmask_b32_e64 v30, v31, v30, s[40:41]
	v_mad_i64_i32 v[2:3], s[0:1], v30, s43, v[22:23]
	v_lshl_add_u64 v[2:3], v[2:3], 0, v[26:27]
	v_mov_b32_e32 v8, s100
	v_mov_b32_e32 v9, s101
	s_movk_i32 s43, 0x400
	v_mad_i64_i32 v[22:23], s[0:1], v18, s43, v[242:243]
	v_lshl_add_u64 v[22:23], v[22:23], 0, v[20:21]
	v_mov_b32_e32 v30, v24
	v_sub_u32_e32 v31, 0, v30
	v_cndmask_b32_e64 v30, v31, v30, s[40:41]
	v_mad_i64_i32 v[4:5], s[0:1], v30, s43, v[22:23]
	v_lshl_add_u64 v[4:5], v[4:5], 0, v[26:27]
	v_mov_b32_e32 v10, s98
	v_mov_b32_e32 v11, s99
	s_branch .Lrw_dma_set
.Lrw_dma_lw3:
	s_movk_i32 s43, 0x400
	v_mad_i64_i32 v[22:23], s[0:1], v18, s43, v[242:243]
	v_lshl_add_u64 v[22:23], v[22:23], 0, v[20:21]
	v_add_u32_e32 v30, 8, v24
	v_sub_u32_e32 v31, 0, v30
	v_cndmask_b32_e64 v30, v31, v30, s[40:41]
	v_mad_i64_i32 v[0:1], s[0:1], v30, s43, v[22:23]
	v_lshl_add_u64 v[0:1], v[0:1], 0, v[26:27]
	v_mov_b32_e32 v6, s98
	v_mov_b32_e32 v7, s99
	s_movk_i32 s43, 0x400
	v_mad_i64_i32 v[22:23], s[0:1], v18, s43, v[246:247]
	v_lshl_add_u64 v[22:23], v[22:23], 0, v[20:21]
	v_mov_b32_e32 v30, v24
	v_sub_u32_e32 v31, 0, v30
	v_cndmask_b32_e64 v30, v31, v30, s[40:41]
	v_mad_i64_i32 v[2:3], s[0:1], v30, s43, v[22:23]
	v_lshl_add_u64 v[2:3], v[2:3], 0, v[26:27]
	v_mov_b32_e32 v8, s98
	v_mov_b32_e32 v9, s99
	s_movk_i32 s43, 0x400
	v_mad_i64_i32 v[22:23], s[0:1], v18, s43, v[246:247]
	v_lshl_add_u64 v[22:23], v[22:23], 0, v[20:21]
	v_add_u32_e32 v30, 8, v24
	v_sub_u32_e32 v31, 0, v30
	v_cndmask_b32_e64 v30, v31, v30, s[40:41]
	v_mad_i64_i32 v[4:5], s[0:1], v30, s43, v[22:23]
	v_lshl_add_u64 v[4:5], v[4:5], 0, v[26:27]
	v_mov_b32_e32 v10, s98
	v_mov_b32_e32 v11, s99
.Lrw_dma_set:
	s_mul_i32 s100, s42, 0xc00
	s_add_i32 s100, s100, 0x15800
	v_sub_co_u32_e32 v0, vcc, v0, v6
	v_subb_co_u32_e32 v1, vcc, v1, v7, vcc
	v_sub_co_u32_e32 v2, vcc, v2, v8
	v_subb_co_u32_e32 v3, vcc, v3, v9, vcc
	v_sub_co_u32_e32 v4, vcc, v4, v10
	v_subb_co_u32_e32 v5, vcc, v5, v11, vcc
	s_add_i32 m0, s100, 0x0
	s_nop 0
	global_load_lds_dwordx4 v[0:1], off
	v_lshl_add_u64 v[0:1], v[0:1], 0, v[6:7]
	s_add_i32 m0, m0, 0x400
	s_nop 0
	global_load_lds_dwordx4 v[2:3], off
	v_lshl_add_u64 v[2:3], v[2:3], 0, v[8:9]
	s_add_i32 m0, m0, 0x400
	s_nop 0
	global_load_lds_dwordx4 v[4:5], off
	v_lshl_add_u64 v[4:5], v[4:5], 0, v[10:11]
	s_add_i32 m0, s100, 0x3000
	s_nop 0
	global_load_lds_dwordx4 v[0:1], off
	v_lshl_add_u64 v[0:1], v[0:1], 0, v[6:7]
	s_add_i32 m0, m0, 0x400
	s_nop 0
	global_load_lds_dwordx4 v[2:3], off
	v_lshl_add_u64 v[2:3], v[2:3], 0, v[8:9]
	s_add_i32 m0, m0, 0x400
	s_nop 0
	global_load_lds_dwordx4 v[4:5], off
	v_lshl_add_u64 v[4:5], v[4:5], 0, v[10:11]
	s_mov_b32 s98, 0
	s_movk_i32 s99, 0x6000
	s_waitcnt vmcnt(0)
.Lrw_init_done:
	s_barrier
	s_branch .LBB0_614

; __device__ __forceinline__ void unpack4(const u32x2 w, float (&f)[4]) { f[0] = bflo(w.x); f[1] = bfhi(w.x); f[2] = bflo(w.y); f[3] = bfhi(w.y); }
; template <bool RWKV> __device__ __forceinline__ void scan_load_finish(LAS unsigned char* buf, const ScanLd& L, int lt) {
;     const int lw = lt >> 6, lane = lt & 63, sl = lane >> 2, col = 16 * lw + 4 * (lane & 3);
;     float d[4], c[4], k[4], r[4], v[4], kk[4], nb[4];
;     unpack4(L.rd, d); unpack4(L.rk, k); unpack4(L.rr, r); unpack4(L.rv, v); unpack4(L.rkk, kk); unpack4(L.rnb, nb);
; #pragma unroll
;     for (int i = 0; i < 4; ++i) c[i] = d[i];
; #pragma unroll
;     for (int dl = 4; dl < 64; dl <<= 1)
; #pragma unroll
;         for (int i = 0; i < 4; ++i) { const float t = __shfl_up(c[i], dl); c[i] += (lane >= dl) ? t : 0.f; }
;     float o1[4], o2[4], o3[4], o4[4]; f32x4 we;
; #pragma unroll
;     for (int i = 0; i < 4; ++i) { const float W = __expf(-c[i]), iW = __expf(c[i]), Wp = __expf(d[i] - c[i]); o1[i] = RWKV ? kk[i] * Wp : 0.f; o2[i] = RWKV ? nb[i] * iW : 0.f; o3[i] = k[i] * iW; o4[i] = r[i] * W; we[i] = W; }
;     u32x2 w;
;     w.x = cvt2(o1[0], o1[1]); w.y = cvt2(o1[2], o1[3]); *(LAS u32x2*)(buf + SB_XA + sl * 144 + col * 2) = w;
;     w.x = cvt2(o4[0], o4[1]); w.y = cvt2(o4[2], o4[3]); *(LAS u32x2*)(buf + SB_XA + (16 + sl) * 144 + col * 2) = w;
;     w.x = cvt2(o2[0], o2[1]); w.y = cvt2(o2[2], o2[3]); *(LAS u32x2*)(buf + SB_XB + sl * 144 + col * 2) = w;
;     w.x = cvt2(o3[0], o3[1]); w.y = cvt2(o3[2], o3[3]); *(LAS u32x2*)(buf + SB_XB + (16 + sl) * 144 + col * 2) = w;
; #pragma unroll
;     for (int i = 0; i < 4; ++i) {
;         *(LAS unsigned short*)(buf + SB_XBT + (col + i) * 80 + sl * 2) = (unsigned short)(cvt2(o2[i], 0.f) & 0xffffu);
;         *(LAS unsigned short*)(buf + SB_XBT + (col + i) * 80 + (16 + sl) * 2) = (unsigned short)(cvt2(o3[i], 0.f) & 0xffffu);
;         *(LAS unsigned short*)(buf + SB_VT + (col + i) * 48 + sl * 2) = (unsigned short)(cvt2(v[i], 0.f) & 0xffffu); }
;     if (sl == SC_CH - 1) *(LAS f32x4*)(buf + SB_WE + col * 4) = we;
; }
; template <bool RWKV> __device__ __forceinline__ void scan_item(LAS unsigned char* lds, const ScanSrc& S, int wid, int lane) {
;     ...
;         if (is_ld) {
;             if (c + 3 < NCH) scan_load_finish<RWKV>(lds + ((b0 + 3) & 3) * SC_BUF, L, lt);
;             if (c + 4 < NCH) scan_load_issue<RWKV>(L, S, c + 4, lt); }
.LBB0_640:
	s_cmpk_gt_u32 s69, 0xfc
	s_cbranch_scc1 .LBB0_613
	v_add_u32_e32 v13, s98, v12
	ds_read_b64 v[76:77], v13
	ds_read_b64 v[78:79], v13 offset:2048
	ds_read_b64 v[80:81], v13 offset:4096
	ds_read_b64 v[82:83], v13 offset:6144
	ds_read_b64 v[84:85], v13 offset:8192
	ds_read_b64 v[86:87], v13 offset:10240
	s_add_i32 s0, s70, -1
	s_and_b32 s0, s0, 3
	s_mulk_i32 s0, 0x4500
	v_add_u32_e32 v190, s0, v250
	s_add_i32 s98, s98, 0x3000
	s_cmp_eq_u32 s98, 0x9000
	s_cselect_b32 s98, 0, s98
	s_cmpk_gt_u32 s69, 0xfa
	s_cbranch_scc1 .Lrw_nodma
	s_add_i32 m0, s100, s99
	s_add_i32 s99, s99, 0x3000
	s_cmp_eq_u32 s99, 0x9000
	s_cselect_b32 s99, 0, s99
	global_load_lds_dwordx4 v[0:1], off
	s_add_i32 m0, m0, 0x400
	v_lshl_add_u64 v[0:1], v[0:1], 0, v[6:7]
	global_load_lds_dwordx4 v[2:3], off
	s_add_i32 m0, m0, 0x400
	v_lshl_add_u64 v[2:3], v[2:3], 0, v[8:9]
	global_load_lds_dwordx4 v[4:5], off
	v_lshl_add_u64 v[4:5], v[4:5], 0, v[10:11]
.Lrw_nodma:
	s_waitcnt lgkmcnt(0)
	v_lshlrev_b32_e32 v32, 16, v76
	v_and_b32_e32 v33, 0xffff0000, v76
	v_lshlrev_b32_e32 v34, 16, v77
	v_and_b32_e32 v35, 0xffff0000, v77
	v_mul_f32_e32 v52, 0x3fb8aa3b, v32
	v_mul_f32_e32 v53, 0x3fb8aa3b, v33
	v_mul_f32_e32 v54, 0x3fb8aa3b, v34
	v_mul_f32_e32 v55, 0x3fb8aa3b, v35
	v_add_f32_dpp v52, v52, v52 row_shr:4 row_mask:0xf bank_mask:0xf
	v_add_f32_dpp v53, v53, v53 row_shr:4 row_mask:0xf bank_mask:0xf
	v_add_f32_dpp v54, v54, v54 row_shr:4 row_mask:0xf bank_mask:0xf
	v_add_f32_dpp v55, v55, v55 row_shr:4 row_mask:0xf bank_mask:0xf
	v_add_f32_dpp v52, v52, v52 row_shr:8 row_mask:0xf bank_mask:0xf
	v_add_f32_dpp v53, v53, v53 row_shr:8 row_mask:0xf bank_mask:0xf
	v_add_f32_dpp v54, v54, v54 row_shr:8 row_mask:0xf bank_mask:0xf
	v_add_f32_dpp v55, v55, v55 row_shr:8 row_mask:0xf bank_mask:0xf
	ds_bpermute_b32 v60, v251, v52
	ds_bpermute_b32 v61, v251, v53
	ds_bpermute_b32 v62, v251, v54
	ds_bpermute_b32 v63, v251, v55
	ds_write_b16 v190, v82 offset:14336
	ds_write_b16_d16_hi v190, v82 offset:14384
	ds_write_b16 v190, v83 offset:14432
	ds_write_b16_d16_hi v190, v83 offset:14480
	v_lshlrev_b32_e32 v36, 16, v78
	v_and_b32_e32 v37, 0xffff0000, v78
	v_lshlrev_b32_e32 v38, 16, v79
	v_and_b32_e32 v39, 0xffff0000, v79
	v_lshlrev_b32_e32 v40, 16, v80
	v_and_b32_e32 v41, 0xffff0000, v80
	v_lshlrev_b32_e32 v42, 16, v81
	v_and_b32_e32 v43, 0xffff0000, v81
	v_lshlrev_b32_e32 v44, 16, v84
	v_and_b32_e32 v45, 0xffff0000, v84
	v_lshlrev_b32_e32 v46, 16, v85
	v_and_b32_e32 v47, 0xffff0000, v85
	v_lshlrev_b32_e32 v48, 16, v86
	v_and_b32_e32 v49, 0xffff0000, v86
	v_lshlrev_b32_e32 v50, 16, v87
	v_and_b32_e32 v51, 0xffff0000, v87
	s_waitcnt lgkmcnt(4)
	v_fmac_f32_e32 v52, v60, v253
	v_fmac_f32_e32 v53, v61, v253
	v_fmac_f32_e32 v54, v62, v253
	v_fmac_f32_e32 v55, v63, v253
	ds_bpermute_b32 v60, v252, v52
	ds_bpermute_b32 v61, v252, v53
	ds_bpermute_b32 v62, v252, v54
	ds_bpermute_b32 v63, v252, v55
	s_waitcnt lgkmcnt(0)
	v_fmac_f32_e32 v52, v60, v245
	v_fmac_f32_e32 v53, v61, v245
	v_fmac_f32_e32 v54, v62, v245
	v_fmac_f32_e32 v55, v63, v245
.Lrw_ldfin:
	v_fmamk_f32 v56, v32, 0xbfb8aa3b, v52
	v_fmamk_f32 v57, v33, 0xbfb8aa3b, v53
	v_fmamk_f32 v58, v34, 0xbfb8aa3b, v54
	v_fmamk_f32 v59, v35, 0xbfb8aa3b, v55
	v_exp_f32_e64 v64, -v52
	v_exp_f32_e64 v65, -v53
	v_exp_f32_e64 v66, -v54
	v_exp_f32_e64 v67, -v55
	v_exp_f32_e32 v68, v52
	v_exp_f32_e32 v69, v53
	v_exp_f32_e32 v70, v54
	v_exp_f32_e32 v71, v55
	v_exp_f32_e64 v192, -v56
	v_exp_f32_e64 v193, -v57
	v_exp_f32_e64 v194, -v58
	v_exp_f32_e64 v195, -v59
	v_add_u32_e32 v191, s0, v248
	v_pk_mul_f32 v[208:209], v[64:65], v[40:41]
	v_pk_mul_f32 v[210:211], v[66:67], v[42:43]
	v_pk_mul_f32 v[200:201], v[68:69], v[48:49]
	v_pk_mul_f32 v[202:203], v[70:71], v[50:51]
	v_pk_mul_f32 v[204:205], v[68:69], v[36:37]
	v_pk_mul_f32 v[206:207], v[70:71], v[38:39]
	v_pk_mul_f32 v[196:197], v[192:193], v[44:45]
	v_pk_mul_f32 v[198:199], v[194:195], v[46:47]
	v_cvt_pk_bf16_f32 v218, v208, v209
	v_cvt_pk_bf16_f32 v219, v210, v211
	v_cvt_pk_bf16_f32 v214, v200, v201
	v_cvt_pk_bf16_f32 v215, v202, v203
	v_cvt_pk_bf16_f32 v216, v204, v205
	v_cvt_pk_bf16_f32 v217, v206, v207
	v_cvt_pk_bf16_f32 v212, v196, v197
	v_cvt_pk_bf16_f32 v213, v198, v199
	v_add_u32_e32 v220, 0x900, v191
	v_add_u32_e32 v221, s0, v249
	ds_write2st64_b64 v220, v[218:219], v[216:217] offset1:9
	ds_write2st64_b64 v191, v[212:213], v[214:215] offset1:9
	ds_write_b16 v221, v214 offset:9216
	ds_write_b16_d16_hi v221, v214 offset:9296
	ds_write_b16 v221, v215 offset:9376
	ds_write_b16_d16_hi v221, v215 offset:9456
	ds_write_b16 v221, v216 offset:9248
	ds_write_b16_d16_hi v221, v216 offset:9328
	ds_write_b16 v221, v217 offset:9408
	ds_write_b16_d16_hi v221, v217 offset:9488
	s_and_saveexec_b64 s[42:43], s[14:15]
	v_add_u32_e32 v60, s0, v188
	ds_write_b128 v60, v[64:67] offset:17408
	s_or_b64 exec, exec, s[42:43]
	s_cmpk_gt_u32 s69, 0xfa
	s_cbranch_scc1 .Lrw_dma_drain
	s_waitcnt vmcnt(3)
	s_branch .LBB0_613
.Lrw_dma_drain:
	s_waitcnt vmcnt(0)
	s_branch .LBB0_613
